# K-loop bodies of in-proj/up/final-down: constant landed-flag control flow folded (14 SALU/VALU/branch instrs per iteration removed, waits unconditional), later code placement kept identical (on pack_m
# baseline (speedup 1.0000x reference)
; #define PG8_STAGE(bufoff, gbase, voff) glds16s2((voff)[0], (voff)[1], (const void*)(gbase), ldsn + (unsigned)(bufoff))
; #define PG8_LDA(dst, b, h) do { _Pragma("unroll") for (int m = 0; m < 4; ++m) _Pragma("unroll") for (int k = 0; k < 2; ++k) dst[m][k] = *(const LAS bf16x8*)(lds + PG8_SA(b, h) + aoff + m * 2048 + k * 1024); } while (0)
; #define PG8_LDB(dst, b, h) do { _Pragma("unroll") for (int n = 0; n < 2; ++n) _Pragma("unroll") for (int k = 0; k < 2; ++k) dst[n][k] = *(const LAS bf16x8*)(lds + PG8_SB(b, h) + boff + n * 2048 + k * 1024); } while (0)
; #define PG8_MMA(ai, bj, At, Bt) do { __builtin_amdgcn_s_setprio(1); _Pragma("unroll") for (int m = 0; m < 4; ++m) _Pragma("unroll") for (int n = 0; n < 2; ++n) _Pragma("unroll") for (int k = 0; k < 2; ++k) \
;         acc[ai][bj][m][n] = __builtin_amdgcn_mfma_f32_16x16x32_bf16(Bt[n][k], At[m][k], acc[ai][bj][m][n], 0, 0, 0); __builtin_amdgcn_s_setprio(0); } while (0)
; #define PG8_WAIT_V(n) asm volatile("s_waitcnt vmcnt(" #n ")" ::: "memory")
; #define PG8_WAIT_L(n) asm volatile("s_waitcnt lgkmcnt(" #n ")" ::: "memory")
; #define PG8_BAR __builtin_amdgcn_s_barrier()
; #define PG8_SCHED __builtin_amdgcn_sched_barrier(0)
; template <class Epi, bool ALIGN_EPI, bool EARLY_DRAIN = true, class Pre = NoPre>
; __device__ __forceinline__ void gemm_phase(LAS unsigned char* lds, const Gemm g, const StaticOrder& S, const Epi& E, int wv, const Pre& pre = Pre()) {
;     ...
;             const char* a1 = cA + (size_t)(t + 1) * kstep;
;             const char* a2 = last ? nA : cA + (size_t)(t + 2) * kstep; const char* b2 = last ? nB : cB + (size_t)(t + 2) * kstep;
;             const char* a3 = a2 + kstep; const char* b3 = b2 + kstep;
;             int lf_ = EARLY_DRAIN ? __builtin_amdgcn_readfirstlane(landed_flag) : landed_flag; if constexpr (EARLY_DRAIN) asm volatile("" : "+s"(lf_)); landed_flag = 0;
;             PG8_LDB(B0, 0, 0); PG8_LDB(B1, 0, 1); PG8_SCHED; PG8_LDA(At, 0, 0); PG8_STAGE(PG8_SA(1, 1), a1 + ahs, voffA);
;             if (!lf_) PG8_WAIT_V(8);
;             PG8_WAIT_L(0); PG8_BAR; PG8_MMA(0, 0, At, B0); PG8_MMA(0, 1, At, B1); PG8_BAR; PG8_SCHED;
;             PG8_LDA(At, 0, 1); PG8_STAGE(PG8_SB(0, 0), b2, voffB); PG8_STAGE(PG8_SB(0, 1), b2 + bhs, voffB); PG8_STAGE(PG8_SA(0, 0), a2, voffA);
;             if (!lf_) PG8_WAIT_V(8);
.LBB0_178:
	ds_read_b128 v[146:149], v245
	ds_read_b128 v[150:153], v245 offset:1024
	ds_read_b128 v[154:157], v245 offset:2048
	ds_read_b128 v[158:161], v245 offset:3072
	ds_read_b128 v[130:133], v246
	ds_read_b128 v[134:137], v246 offset:1024
	ds_read_b128 v[138:141], v246 offset:2048
	ds_read_b128 v[142:145], v246 offset:3072
	ds_read_b128 v[186:189], v244
	ds_read_b128 v[190:193], v244 offset:1024
	ds_read_b128 v[178:181], v244 offset:2048
	ds_read_b128 v[182:185], v244 offset:3072
	ds_read_b128 v[170:173], v244 offset:4096
	ds_read_b128 v[174:177], v244 offset:5120
	ds_read_b128 v[162:165], v244 offset:6144
	ds_read_b128 v[166:169], v244 offset:7168
	s_mov_b32 m0, s26
	s_nop 0
	global_load_lds_dwordx4 v0, s[68:69]
	s_add_u32 m0, m0, 0x2000
	s_nop 0
	global_load_lds_dwordx4 v231, s[68:69]
	s_waitcnt vmcnt(8)
.LBB0_180:
	s_waitcnt lgkmcnt(0)
	s_cmp_eq_u32 s64, 12
	s_cselect_b32 s85, s61, s51
	s_cselect_b32 s84, s60, s50
	s_cselect_b32 s71, s43, s53
	s_cselect_b32 s70, s47, s52
	s_barrier
	s_setprio 1
	s_waitcnt lgkmcnt(7)
	v_mfma_f32_16x16x32_bf16 v[122:125], v[146:149], v[186:189], v[122:125]
	v_mfma_f32_16x16x32_bf16 v[114:117], v[154:157], v[186:189], v[114:117]
	s_waitcnt lgkmcnt(5)
	v_mfma_f32_16x16x32_bf16 v[106:109], v[146:149], v[178:181], v[106:109]
	v_mfma_f32_16x16x32_bf16 v[98:101], v[154:157], v[178:181], v[98:101]
	s_waitcnt lgkmcnt(3)
	v_mfma_f32_16x16x32_bf16 v[90:93], v[146:149], v[170:173], v[90:93]
	v_mfma_f32_16x16x32_bf16 v[82:85], v[154:157], v[170:173], v[82:85]
	s_waitcnt lgkmcnt(1)
	v_mfma_f32_16x16x32_bf16 v[62:65], v[146:149], v[162:165], v[62:65]
	v_mfma_f32_16x16x32_bf16 v[50:53], v[154:157], v[162:165], v[50:53]
	v_mfma_f32_16x16x32_bf16 v[122:125], v[150:153], v[190:193], v[122:125]
	v_mfma_f32_16x16x32_bf16 v[114:117], v[158:161], v[190:193], v[114:117]
	v_mfma_f32_16x16x32_bf16 v[106:109], v[150:153], v[182:185], v[106:109]
	v_mfma_f32_16x16x32_bf16 v[98:101], v[158:161], v[182:185], v[98:101]
	v_mfma_f32_16x16x32_bf16 v[90:93], v[150:153], v[174:177], v[90:93]
	v_mfma_f32_16x16x32_bf16 v[82:85], v[158:161], v[174:177], v[82:85]
	s_waitcnt lgkmcnt(0)
	v_mfma_f32_16x16x32_bf16 v[62:65], v[150:153], v[166:169], v[62:65]
	v_mfma_f32_16x16x32_bf16 v[50:53], v[158:161], v[166:169], v[50:53]
	s_setprio 0
	s_setprio 1
	v_mfma_f32_16x16x32_bf16 v[126:129], v[130:133], v[186:189], v[126:129]
	v_mfma_f32_16x16x32_bf16 v[118:121], v[138:141], v[186:189], v[118:121]
	v_mfma_f32_16x16x32_bf16 v[110:113], v[130:133], v[178:181], v[110:113]
	v_mfma_f32_16x16x32_bf16 v[102:105], v[138:141], v[178:181], v[102:105]
	v_mfma_f32_16x16x32_bf16 v[94:97], v[130:133], v[170:173], v[94:97]
	v_mfma_f32_16x16x32_bf16 v[86:89], v[138:141], v[170:173], v[86:89]
	v_mfma_f32_16x16x32_bf16 v[70:73], v[130:133], v[162:165], v[70:73]
	v_mfma_f32_16x16x32_bf16 v[54:57], v[138:141], v[162:165], v[54:57]
	v_mfma_f32_16x16x32_bf16 v[126:129], v[134:137], v[190:193], v[126:129]
	v_mfma_f32_16x16x32_bf16 v[118:121], v[142:145], v[190:193], v[118:121]
	v_mfma_f32_16x16x32_bf16 v[110:113], v[134:137], v[182:185], v[110:113]
	v_mfma_f32_16x16x32_bf16 v[102:105], v[142:145], v[182:185], v[102:105]
	v_mfma_f32_16x16x32_bf16 v[94:97], v[134:137], v[174:177], v[94:97]
	v_mfma_f32_16x16x32_bf16 v[86:89], v[142:145], v[174:177], v[86:89]
	v_mfma_f32_16x16x32_bf16 v[70:73], v[134:137], v[166:169], v[70:73]
	v_mfma_f32_16x16x32_bf16 v[54:57], v[142:145], v[166:169], v[54:57]
	s_setprio 0
	s_barrier
	ds_read_b128 v[186:189], v244 offset:16384
	ds_read_b128 v[190:193], v244 offset:17408
	ds_read_b128 v[178:181], v244 offset:18432
	ds_read_b128 v[182:185], v244 offset:19456
	ds_read_b128 v[170:173], v244 offset:20480
	ds_read_b128 v[174:177], v244 offset:21504
	ds_read_b128 v[162:165], v244 offset:22528
	ds_read_b128 v[166:169], v244 offset:23552
	s_mov_b32 m0, s10
	s_nop 0
	global_load_lds_dwordx4 v230, s[70:71]
	s_add_u32 m0, m0, 0x2000
	s_nop 0
	global_load_lds_dwordx4 v232, s[70:71]
	s_add_u32 s36, s70, 0x40000
	s_addc_u32 s37, s71, 0
	s_mov_b32 m0, s12
	s_nop 0
	global_load_lds_dwordx4 v230, s[36:37]
	s_add_u32 m0, m0, 0x2000
	s_nop 0
	global_load_lds_dwordx4 v232, s[36:37]
	s_mov_b32 m0, s5
	s_nop 0
	global_load_lds_dwordx4 v0, s[84:85]
	s_add_u32 m0, m0, 0x2000
	s_nop 0
	global_load_lds_dwordx4 v231, s[84:85]
	s_waitcnt vmcnt(8)
; #define PG8_STAGE(bufoff, gbase, voff) glds16s2((voff)[0], (voff)[1], (const void*)(gbase), ldsn + (unsigned)(bufoff))
; #define PG8_LDA(dst, b, h) do { _Pragma("unroll") for (int m = 0; m < 4; ++m) _Pragma("unroll") for (int k = 0; k < 2; ++k) dst[m][k] = *(const LAS bf16x8*)(lds + PG8_SA(b, h) + aoff + m * 2048 + k * 1024); } while (0)
; #define PG8_LDB(dst, b, h) do { _Pragma("unroll") for (int n = 0; n < 2; ++n) _Pragma("unroll") for (int k = 0; k < 2; ++k) dst[n][k] = *(const LAS bf16x8*)(lds + PG8_SB(b, h) + boff + n * 2048 + k * 1024); } while (0)
; #define PG8_MMA(ai, bj, At, Bt) do { __builtin_amdgcn_s_setprio(1); _Pragma("unroll") for (int m = 0; m < 4; ++m) _Pragma("unroll") for (int n = 0; n < 2; ++n) _Pragma("unroll") for (int k = 0; k < 2; ++k) \
;         acc[ai][bj][m][n] = __builtin_amdgcn_mfma_f32_16x16x32_bf16(Bt[n][k], At[m][k], acc[ai][bj][m][n], 0, 0, 0); __builtin_amdgcn_s_setprio(0); } while (0)
; #define PG8_WAIT_V(n) asm volatile("s_waitcnt vmcnt(" #n ")" ::: "memory")
; #define PG8_WAIT_L(n) asm volatile("s_waitcnt lgkmcnt(" #n ")" ::: "memory")
; #define PG8_BAR __builtin_amdgcn_s_barrier()
; #define PG8_SCHED __builtin_amdgcn_sched_barrier(0)
; template <class Epi, bool ALIGN_EPI, bool EARLY_DRAIN = true, class Pre = NoPre>
; __device__ __forceinline__ void gemm_phase(LAS unsigned char* lds, const Gemm g, const StaticOrder& S, const Epi& E, int wv, const Pre& pre = Pre()) {
;     ...
;             PG8_WAIT_L(0); PG8_BAR; PG8_MMA(1, 0, At, B0); PG8_MMA(1, 1, At, B1); PG8_BAR; PG8_SCHED;
;             PG8_LDB(B0, 1, 0); PG8_LDB(B1, 1, 1); PG8_SCHED; PG8_LDA(At, 1, 0); PG8_STAGE(PG8_SA(0, 1), a2 + ahs, voffA);
;             if (!lf_) PG8_WAIT_V(8);
.LBB0_182:
	s_waitcnt lgkmcnt(0)
	s_barrier
	s_setprio 1
	s_waitcnt lgkmcnt(7)
	v_mfma_f32_16x16x32_bf16 v[74:77], v[146:149], v[186:189], v[74:77]
	v_mfma_f32_16x16x32_bf16 v[58:61], v[154:157], v[186:189], v[58:61]
	s_waitcnt lgkmcnt(5)
	v_mfma_f32_16x16x32_bf16 v[42:45], v[146:149], v[178:181], v[42:45]
	v_mfma_f32_16x16x32_bf16 v[34:37], v[154:157], v[178:181], v[34:37]
	s_waitcnt lgkmcnt(3)
	v_mfma_f32_16x16x32_bf16 v[26:29], v[146:149], v[170:173], v[26:29]
	v_mfma_f32_16x16x32_bf16 v[18:21], v[154:157], v[170:173], v[18:21]
	s_waitcnt lgkmcnt(1)
	v_mfma_f32_16x16x32_bf16 v[10:13], v[146:149], v[162:165], v[10:13]
	v_mfma_f32_16x16x32_bf16 v[2:5], v[154:157], v[162:165], v[2:5]
	v_mfma_f32_16x16x32_bf16 v[74:77], v[150:153], v[190:193], v[74:77]
	v_mfma_f32_16x16x32_bf16 v[58:61], v[158:161], v[190:193], v[58:61]
	v_mfma_f32_16x16x32_bf16 v[42:45], v[150:153], v[182:185], v[42:45]
	v_mfma_f32_16x16x32_bf16 v[34:37], v[158:161], v[182:185], v[34:37]
	v_mfma_f32_16x16x32_bf16 v[26:29], v[150:153], v[174:177], v[26:29]
	v_mfma_f32_16x16x32_bf16 v[18:21], v[158:161], v[174:177], v[18:21]
	s_waitcnt lgkmcnt(0)
	v_mfma_f32_16x16x32_bf16 v[10:13], v[150:153], v[166:169], v[10:13]
	v_mfma_f32_16x16x32_bf16 v[2:5], v[158:161], v[166:169], v[2:5]
	s_setprio 0
	s_setprio 1
	v_mfma_f32_16x16x32_bf16 v[78:81], v[130:133], v[186:189], v[78:81]
	v_mfma_f32_16x16x32_bf16 v[66:69], v[138:141], v[186:189], v[66:69]
	v_mfma_f32_16x16x32_bf16 v[46:49], v[130:133], v[178:181], v[46:49]
	v_mfma_f32_16x16x32_bf16 v[38:41], v[138:141], v[178:181], v[38:41]
	v_mfma_f32_16x16x32_bf16 v[30:33], v[130:133], v[170:173], v[30:33]
	v_mfma_f32_16x16x32_bf16 v[22:25], v[138:141], v[170:173], v[22:25]
	v_mfma_f32_16x16x32_bf16 v[14:17], v[130:133], v[162:165], v[14:17]
	v_mfma_f32_16x16x32_bf16 v[6:9], v[138:141], v[162:165], v[6:9]
	v_mfma_f32_16x16x32_bf16 v[78:81], v[134:137], v[190:193], v[78:81]
	v_mfma_f32_16x16x32_bf16 v[66:69], v[142:145], v[190:193], v[66:69]
	v_mfma_f32_16x16x32_bf16 v[46:49], v[134:137], v[182:185], v[46:49]
	v_mfma_f32_16x16x32_bf16 v[38:41], v[142:145], v[182:185], v[38:41]
	v_mfma_f32_16x16x32_bf16 v[30:33], v[134:137], v[174:177], v[30:33]
	v_mfma_f32_16x16x32_bf16 v[22:25], v[142:145], v[174:177], v[22:25]
	v_mfma_f32_16x16x32_bf16 v[14:17], v[134:137], v[166:169], v[14:17]
	v_mfma_f32_16x16x32_bf16 v[6:9], v[142:145], v[166:169], v[6:9]
	s_setprio 0
	s_barrier
	ds_read_b128 v[146:149], v234
	ds_read_b128 v[150:153], v234 offset:1024
	ds_read_b128 v[154:157], v234 offset:2048
	ds_read_b128 v[158:161], v234 offset:3072
	ds_read_b128 v[130:133], v235
	ds_read_b128 v[134:137], v235 offset:1024
	ds_read_b128 v[138:141], v235 offset:2048
	ds_read_b128 v[142:145], v235 offset:3072
	ds_read_b128 v[186:189], v244 offset:32768
	ds_read_b128 v[190:193], v244 offset:33792
	ds_read_b128 v[178:181], v244 offset:34816
	ds_read_b128 v[182:185], v244 offset:35840
	ds_read_b128 v[170:173], v244 offset:36864
	ds_read_b128 v[174:177], v244 offset:37888
	ds_read_b128 v[162:165], v244 offset:38912
	ds_read_b128 v[166:169], v244 offset:39936
	s_add_u32 s66, s84, 0x40000
	s_addc_u32 s67, s85, 0
	s_mov_b32 m0, s13
	s_nop 0
	global_load_lds_dwordx4 v0, s[66:67]
	s_add_u32 m0, m0, 0x2000
	s_nop 0
	global_load_lds_dwordx4 v231, s[66:67]
	s_waitcnt vmcnt(8)
	s_branch .LBB0_177
	s_nop 0
	s_nop 0
	s_nop 0
	s_nop 0
	s_nop 0
	s_nop 0
	s_nop 0
	s_nop 0
	s_nop 0
	s_nop 0
	s_nop 0
	s_nop 0
	s_nop 0

; #define PG8_STAGE(bufoff, gbase, voff) glds16s2((voff)[0], (voff)[1], (const void*)(gbase), ldsn + (unsigned)(bufoff))
; #define PG8_LDA(dst, b, h) do { _Pragma("unroll") for (int m = 0; m < 4; ++m) _Pragma("unroll") for (int k = 0; k < 2; ++k) dst[m][k] = *(const LAS bf16x8*)(lds + PG8_SA(b, h) + aoff + m * 2048 + k * 1024); } while (0)
; #define PG8_LDB(dst, b, h) do { _Pragma("unroll") for (int n = 0; n < 2; ++n) _Pragma("unroll") for (int k = 0; k < 2; ++k) dst[n][k] = *(const LAS bf16x8*)(lds + PG8_SB(b, h) + boff + n * 2048 + k * 1024); } while (0)
; #define PG8_MMA(ai, bj, At, Bt) do { __builtin_amdgcn_s_setprio(1); _Pragma("unroll") for (int m = 0; m < 4; ++m) _Pragma("unroll") for (int n = 0; n < 2; ++n) _Pragma("unroll") for (int k = 0; k < 2; ++k) \
;         acc[ai][bj][m][n] = __builtin_amdgcn_mfma_f32_16x16x32_bf16(Bt[n][k], At[m][k], acc[ai][bj][m][n], 0, 0, 0); __builtin_amdgcn_s_setprio(0); } while (0)
; #define PG8_WAIT_V(n) asm volatile("s_waitcnt vmcnt(" #n ")" ::: "memory")
; #define PG8_WAIT_L(n) asm volatile("s_waitcnt lgkmcnt(" #n ")" ::: "memory")
; #define PG8_BAR __builtin_amdgcn_s_barrier()
; #define PG8_SCHED __builtin_amdgcn_sched_barrier(0)
; template <class Epi, bool ALIGN_EPI, bool EARLY_DRAIN = true, class Pre = NoPre>
; __device__ __forceinline__ void gemm_phase(LAS unsigned char* lds, const Gemm g, const StaticOrder& S, const Epi& E, int wv, const Pre& pre = Pre()) {
;     ...
;             const char* a1 = cA + (size_t)(t + 1) * kstep;
;             const char* a2 = last ? nA : cA + (size_t)(t + 2) * kstep; const char* b2 = last ? nB : cB + (size_t)(t + 2) * kstep;
;             const char* a3 = a2 + kstep; const char* b3 = b2 + kstep;
;             int lf_ = EARLY_DRAIN ? __builtin_amdgcn_readfirstlane(landed_flag) : landed_flag; if constexpr (EARLY_DRAIN) asm volatile("" : "+s"(lf_)); landed_flag = 0;
;             PG8_LDB(B0, 0, 0); PG8_LDB(B1, 0, 1); PG8_SCHED; PG8_LDA(At, 0, 0); PG8_STAGE(PG8_SA(1, 1), a1 + ahs, voffA);
;             if (!lf_) PG8_WAIT_V(8);
;             PG8_WAIT_L(0); PG8_BAR; PG8_MMA(0, 0, At, B0); PG8_MMA(0, 1, At, B1); PG8_BAR; PG8_SCHED;
;             PG8_LDA(At, 0, 1); PG8_STAGE(PG8_SB(0, 0), b2, voffB); PG8_STAGE(PG8_SB(0, 1), b2 + bhs, voffB); PG8_STAGE(PG8_SA(0, 0), a2, voffA);
;             if (!lf_) PG8_WAIT_V(8);
.LBB0_559:
	ds_read_b128 v[130:133], v0
	ds_read_b128 v[174:177], v0 offset:1024
	ds_read_b128 v[178:181], v0 offset:2048
	ds_read_b128 v[182:185], v0 offset:3072
	ds_read_b128 v[134:137], v234
	ds_read_b128 v[138:141], v234 offset:1024
	ds_read_b128 v[142:145], v234 offset:2048
	ds_read_b128 v[170:173], v234 offset:3072
	ds_read_b128 v[102:105], v245
	ds_read_b128 v[202:205], v245 offset:1024
	ds_read_b128 v[118:121], v245 offset:2048
	ds_read_b128 v[122:125], v245 offset:3072
	ds_read_b128 v[194:197], v245 offset:4096
	ds_read_b128 v[198:201], v245 offset:5120
	ds_read_b128 v[186:189], v245 offset:6144
	ds_read_b128 v[190:193], v245 offset:7168
	s_mov_b32 m0, s67
	s_nop 0
	global_load_lds_dwordx4 v250, s[42:43]
	s_add_u32 m0, m0, 0x2000
	s_nop 0
	global_load_lds_dwordx4 v246, s[42:43]
	s_waitcnt vmcnt(8)
.LBB0_561:
	s_waitcnt lgkmcnt(0)
	s_cmp_eq_u32 s0, 12
	s_cselect_b32 s87, s71, s52
	s_cselect_b32 s86, s70, s51
	s_cselect_b32 s85, s47, s61
	s_cselect_b32 s84, s50, s53
	s_barrier
	s_setprio 1
	s_waitcnt lgkmcnt(7)
	v_mfma_f32_16x16x32_bf16 v[70:73], v[130:133], v[102:105], v[70:73]
	v_mfma_f32_16x16x32_bf16 v[78:81], v[178:181], v[102:105], v[146:149]
	s_waitcnt lgkmcnt(5)
	v_mfma_f32_16x16x32_bf16 v[74:77], v[130:133], v[118:121], v[74:77]
	v_mfma_f32_16x16x32_bf16 v[92:95], v[178:181], v[118:121], v[150:153]
	s_waitcnt lgkmcnt(3)
	v_mfma_f32_16x16x32_bf16 v[82:85], v[130:133], v[194:197], v[82:85]
	v_mfma_f32_16x16x32_bf16 v[66:69], v[178:181], v[194:197], v[66:69]
	s_waitcnt lgkmcnt(1)
	v_mfma_f32_16x16x32_bf16 v[54:57], v[130:133], v[186:189], v[54:57]
	v_mfma_f32_16x16x32_bf16 v[50:53], v[178:181], v[186:189], v[50:53]
	v_mfma_f32_16x16x32_bf16 v[70:73], v[174:177], v[202:205], v[70:73]
	v_mfma_f32_16x16x32_bf16 v[78:81], v[182:185], v[202:205], v[78:81]
	v_mfma_f32_16x16x32_bf16 v[74:77], v[174:177], v[122:125], v[74:77]
	v_mfma_f32_16x16x32_bf16 v[92:95], v[182:185], v[122:125], v[92:95]
	v_mfma_f32_16x16x32_bf16 v[82:85], v[174:177], v[198:201], v[82:85]
	v_mfma_f32_16x16x32_bf16 v[66:69], v[182:185], v[198:201], v[66:69]
	s_waitcnt lgkmcnt(0)
	v_mfma_f32_16x16x32_bf16 v[54:57], v[174:177], v[190:193], v[54:57]
	v_mfma_f32_16x16x32_bf16 v[50:53], v[182:185], v[190:193], v[50:53]
	s_setprio 0
	s_setprio 1
	v_mfma_f32_16x16x32_bf16 v[96:99], v[134:137], v[118:121], v[98:101]
	v_mfma_f32_16x16x32_bf16 v[118:121], v[142:145], v[118:121], v[158:161]
	v_mfma_f32_16x16x32_bf16 v[86:89], v[134:137], v[102:105], v[88:91]
	v_mfma_f32_16x16x32_bf16 v[102:105], v[142:145], v[102:105], v[154:157]
	v_mfma_f32_16x16x32_bf16 v[96:99], v[138:141], v[122:125], v[96:99]
	v_mfma_f32_16x16x32_bf16 v[118:121], v[170:173], v[122:125], v[118:121]
	v_mfma_f32_16x16x32_bf16 v[122:125], v[134:137], v[194:197], v[126:129]
	v_mfma_f32_16x16x32_bf16 v[110:113], v[142:145], v[194:197], v[110:113]
	v_mfma_f32_16x16x32_bf16 v[62:65], v[134:137], v[186:189], v[62:65]
	v_mfma_f32_16x16x32_bf16 v[58:61], v[142:145], v[186:189], v[58:61]
	v_mfma_f32_16x16x32_bf16 v[86:89], v[138:141], v[202:205], v[86:89]
	v_mfma_f32_16x16x32_bf16 v[102:105], v[170:173], v[202:205], v[102:105]
	v_mfma_f32_16x16x32_bf16 v[122:125], v[138:141], v[198:201], v[122:125]
	v_mfma_f32_16x16x32_bf16 v[110:113], v[170:173], v[198:201], v[110:113]
	v_mfma_f32_16x16x32_bf16 v[62:65], v[138:141], v[190:193], v[62:65]
	v_mfma_f32_16x16x32_bf16 v[58:61], v[170:173], v[190:193], v[58:61]
	s_setprio 0
	s_barrier
	ds_read_b128 v[190:193], v245 offset:16384
	ds_read_b128 v[194:197], v245 offset:17408
	ds_read_b128 v[158:161], v245 offset:18432
	ds_read_b128 v[186:189], v245 offset:19456
	ds_read_b128 v[150:153], v245 offset:20480
	ds_read_b128 v[154:157], v245 offset:21504
	ds_read_b128 v[126:129], v245 offset:22528
	ds_read_b128 v[146:149], v245 offset:23552
	s_mov_b32 m0, s22
	s_nop 0
	global_load_lds_dwordx4 v251, s[84:85]
	s_add_u32 m0, m0, 0x2000
	s_nop 0
	global_load_lds_dwordx4 v247, s[84:85]
	s_add_u32 s14, s84, 0x580000
	s_addc_u32 s15, s85, 0
	s_mov_b32 m0, s23
	s_nop 0
	global_load_lds_dwordx4 v251, s[14:15]
	s_add_u32 m0, m0, 0x2000
	s_nop 0
	global_load_lds_dwordx4 v247, s[14:15]
	s_mov_b32 m0, s13
	s_nop 0
	global_load_lds_dwordx4 v250, s[86:87]
	s_add_u32 m0, m0, 0x2000
	s_nop 0
	global_load_lds_dwordx4 v246, s[86:87]
	s_waitcnt vmcnt(8)
; #define PG8_STAGE(bufoff, gbase, voff) glds16s2((voff)[0], (voff)[1], (const void*)(gbase), ldsn + (unsigned)(bufoff))
; #define PG8_LDA(dst, b, h) do { _Pragma("unroll") for (int m = 0; m < 4; ++m) _Pragma("unroll") for (int k = 0; k < 2; ++k) dst[m][k] = *(const LAS bf16x8*)(lds + PG8_SA(b, h) + aoff + m * 2048 + k * 1024); } while (0)
; #define PG8_LDB(dst, b, h) do { _Pragma("unroll") for (int n = 0; n < 2; ++n) _Pragma("unroll") for (int k = 0; k < 2; ++k) dst[n][k] = *(const LAS bf16x8*)(lds + PG8_SB(b, h) + boff + n * 2048 + k * 1024); } while (0)
; #define PG8_MMA(ai, bj, At, Bt) do { __builtin_amdgcn_s_setprio(1); _Pragma("unroll") for (int m = 0; m < 4; ++m) _Pragma("unroll") for (int n = 0; n < 2; ++n) _Pragma("unroll") for (int k = 0; k < 2; ++k) \
;         acc[ai][bj][m][n] = __builtin_amdgcn_mfma_f32_16x16x32_bf16(Bt[n][k], At[m][k], acc[ai][bj][m][n], 0, 0, 0); __builtin_amdgcn_s_setprio(0); } while (0)
; #define PG8_WAIT_V(n) asm volatile("s_waitcnt vmcnt(" #n ")" ::: "memory")
; #define PG8_WAIT_L(n) asm volatile("s_waitcnt lgkmcnt(" #n ")" ::: "memory")
; #define PG8_BAR __builtin_amdgcn_s_barrier()
; #define PG8_SCHED __builtin_amdgcn_sched_barrier(0)
; template <class Epi, bool ALIGN_EPI, bool EARLY_DRAIN = true, class Pre = NoPre>
; __device__ __forceinline__ void gemm_phase(LAS unsigned char* lds, const Gemm g, const StaticOrder& S, const Epi& E, int wv, const Pre& pre = Pre()) {
;     ...
;             PG8_WAIT_L(0); PG8_BAR; PG8_MMA(1, 0, At, B0); PG8_MMA(1, 1, At, B1); PG8_BAR; PG8_SCHED;
;             PG8_LDB(B0, 1, 0); PG8_LDB(B1, 1, 1); PG8_SCHED; PG8_LDA(At, 1, 0); PG8_STAGE(PG8_SA(0, 1), a2 + ahs, voffA);
;             if (!lf_) PG8_WAIT_V(8);
.LBB0_563:
	s_waitcnt lgkmcnt(0)
	s_barrier
	s_setprio 1
	s_waitcnt lgkmcnt(7)
	v_mfma_f32_16x16x32_bf16 v[38:41], v[130:133], v[190:193], v[38:41]
	v_mfma_f32_16x16x32_bf16 v[34:37], v[178:181], v[190:193], v[34:37]
	s_waitcnt lgkmcnt(5)
	v_mfma_f32_16x16x32_bf16 v[26:29], v[130:133], v[158:161], v[26:29]
	v_mfma_f32_16x16x32_bf16 v[18:21], v[178:181], v[158:161], v[18:21]
	s_waitcnt lgkmcnt(3)
	v_mfma_f32_16x16x32_bf16 v[6:9], v[130:133], v[150:153], v[6:9]
	v_mfma_f32_16x16x32_bf16 v[2:5], v[178:181], v[150:153], v[2:5]
	s_waitcnt lgkmcnt(1)
	v_mfma_f32_16x16x32_bf16 v[106:109], v[130:133], v[126:129], v[106:109]
	v_mfma_f32_16x16x32_bf16 v[130:133], v[178:181], v[126:129], v[162:165]
	v_mfma_f32_16x16x32_bf16 v[38:41], v[174:177], v[194:197], v[38:41]
	v_mfma_f32_16x16x32_bf16 v[34:37], v[182:185], v[194:197], v[34:37]
	v_mfma_f32_16x16x32_bf16 v[26:29], v[174:177], v[186:189], v[26:29]
	v_mfma_f32_16x16x32_bf16 v[18:21], v[182:185], v[186:189], v[18:21]
	v_mfma_f32_16x16x32_bf16 v[6:9], v[174:177], v[154:157], v[6:9]
	v_mfma_f32_16x16x32_bf16 v[2:5], v[182:185], v[154:157], v[2:5]
	s_waitcnt lgkmcnt(0)
	v_mfma_f32_16x16x32_bf16 v[106:109], v[174:177], v[146:149], v[106:109]
	v_mfma_f32_16x16x32_bf16 v[130:133], v[182:185], v[146:149], v[130:133]
	s_setprio 0
	s_setprio 1
	v_mfma_f32_16x16x32_bf16 v[46:49], v[134:137], v[190:193], v[46:49]
	v_mfma_f32_16x16x32_bf16 v[42:45], v[142:145], v[190:193], v[42:45]
	v_mfma_f32_16x16x32_bf16 v[30:33], v[134:137], v[158:161], v[30:33]
	v_mfma_f32_16x16x32_bf16 v[22:25], v[142:145], v[158:161], v[22:25]
	v_mfma_f32_16x16x32_bf16 v[14:17], v[134:137], v[150:153], v[14:17]
	v_mfma_f32_16x16x32_bf16 v[10:13], v[142:145], v[150:153], v[10:13]
	v_mfma_f32_16x16x32_bf16 v[114:117], v[134:137], v[126:129], v[114:117]
	v_mfma_f32_16x16x32_bf16 v[126:129], v[142:145], v[126:129], v[166:169]
	v_mfma_f32_16x16x32_bf16 v[46:49], v[138:141], v[194:197], v[46:49]
	v_mfma_f32_16x16x32_bf16 v[42:45], v[170:173], v[194:197], v[42:45]
	v_mfma_f32_16x16x32_bf16 v[30:33], v[138:141], v[186:189], v[30:33]
	v_mfma_f32_16x16x32_bf16 v[22:25], v[170:173], v[186:189], v[22:25]
	v_mfma_f32_16x16x32_bf16 v[14:17], v[138:141], v[154:157], v[14:17]
	v_mfma_f32_16x16x32_bf16 v[10:13], v[170:173], v[154:157], v[10:13]
	v_mfma_f32_16x16x32_bf16 v[114:117], v[138:141], v[146:149], v[114:117]
	v_mfma_f32_16x16x32_bf16 v[134:137], v[170:173], v[146:149], v[126:129]
	s_setprio 0
	s_barrier
	ds_read_b128 v[162:165], v235
	ds_read_b128 v[174:177], v235 offset:1024
	ds_read_b128 v[178:181], v235 offset:2048
	ds_read_b128 v[182:185], v235 offset:3072
	ds_read_b128 v[138:141], v248
	ds_read_b128 v[142:145], v248 offset:1024
	ds_read_b128 v[166:169], v248 offset:2048
	ds_read_b128 v[170:173], v248 offset:3072
	ds_read_b128 v[154:157], v245 offset:32768
	ds_read_b128 v[202:205], v245 offset:33792
	ds_read_b128 v[126:129], v245 offset:34816
	ds_read_b128 v[158:161], v245 offset:35840
	ds_read_b128 v[194:197], v245 offset:36864
	ds_read_b128 v[198:201], v245 offset:37888
	ds_read_b128 v[186:189], v245 offset:38912
	ds_read_b128 v[190:193], v245 offset:39936
	s_add_u32 s14, s86, 0x2000
	s_addc_u32 s15, s87, 0
	s_mov_b32 m0, s45
	s_nop 0
	global_load_lds_dwordx4 v250, s[14:15]
	s_add_u32 m0, m0, 0x2000
	s_nop 0
	global_load_lds_dwordx4 v246, s[14:15]
	s_waitcnt vmcnt(8)
	s_branch .LBB0_558
	s_nop 0
	s_nop 0
	s_nop 0
	s_nop 0
	s_nop 0
	s_nop 0
	s_nop 0
	s_nop 0
	s_nop 0
	s_nop 0
	s_nop 0
	s_nop 0
	s_nop 0

; #define PG8_STAGE(bufoff, gbase, voff) glds16s2((voff)[0], (voff)[1], (const void*)(gbase), ldsn + (unsigned)(bufoff))
; #define PG8_LDA(dst, b, h) do { _Pragma("unroll") for (int m = 0; m < 4; ++m) _Pragma("unroll") for (int k = 0; k < 2; ++k) dst[m][k] = *(const LAS bf16x8*)(lds + PG8_SA(b, h) + aoff + m * 2048 + k * 1024); } while (0)
; #define PG8_LDB(dst, b, h) do { _Pragma("unroll") for (int n = 0; n < 2; ++n) _Pragma("unroll") for (int k = 0; k < 2; ++k) dst[n][k] = *(const LAS bf16x8*)(lds + PG8_SB(b, h) + boff + n * 2048 + k * 1024); } while (0)
; #define PG8_MMA(ai, bj, At, Bt) do { __builtin_amdgcn_s_setprio(1); _Pragma("unroll") for (int m = 0; m < 4; ++m) _Pragma("unroll") for (int n = 0; n < 2; ++n) _Pragma("unroll") for (int k = 0; k < 2; ++k) \
;         acc[ai][bj][m][n] = __builtin_amdgcn_mfma_f32_16x16x32_bf16(Bt[n][k], At[m][k], acc[ai][bj][m][n], 0, 0, 0); __builtin_amdgcn_s_setprio(0); } while (0)
; #define PG8_WAIT_V(n) asm volatile("s_waitcnt vmcnt(" #n ")" ::: "memory")
; #define PG8_WAIT_L(n) asm volatile("s_waitcnt lgkmcnt(" #n ")" ::: "memory")
; #define PG8_BAR __builtin_amdgcn_s_barrier()
; #define PG8_SCHED __builtin_amdgcn_sched_barrier(0)
; template <class Epi, bool ALIGN_EPI, bool EARLY_DRAIN = true, class Pre = NoPre>
; __device__ __forceinline__ void gemm_phase(LAS unsigned char* lds, const Gemm g, const StaticOrder& S, const Epi& E, int wv, const Pre& pre = Pre()) {
;     ...
;             const char* a1 = cA + (size_t)(t + 1) * kstep;
;             const char* a2 = last ? nA : cA + (size_t)(t + 2) * kstep; const char* b2 = last ? nB : cB + (size_t)(t + 2) * kstep;
;             const char* a3 = a2 + kstep; const char* b3 = b2 + kstep;
;             int lf_ = EARLY_DRAIN ? __builtin_amdgcn_readfirstlane(landed_flag) : landed_flag; if constexpr (EARLY_DRAIN) asm volatile("" : "+s"(lf_)); landed_flag = 0;
;             PG8_LDB(B0, 0, 0); PG8_LDB(B1, 0, 1); PG8_SCHED; PG8_LDA(At, 0, 0); PG8_STAGE(PG8_SA(1, 1), a1 + ahs, voffA);
;             if (!lf_) PG8_WAIT_V(8);
;             PG8_WAIT_L(0); PG8_BAR; PG8_MMA(0, 0, At, B0); PG8_MMA(0, 1, At, B1); PG8_BAR; PG8_SCHED;
;             PG8_LDA(At, 0, 1); PG8_STAGE(PG8_SB(0, 0), b2, voffB); PG8_STAGE(PG8_SB(0, 1), b2 + bhs, voffB); PG8_STAGE(PG8_SA(0, 0), a2, voffA);
;             if (!lf_) PG8_WAIT_V(8);
.LBB0_735:
	ds_read_b128 v[158:161], v234
	ds_read_b128 v[166:169], v234 offset:1024
	ds_read_b128 v[170:173], v234 offset:2048
	ds_read_b128 v[174:177], v234 offset:3072
	ds_read_b128 v[134:137], v235
	ds_read_b128 v[138:141], v235 offset:1024
	ds_read_b128 v[142:145], v235 offset:2048
	ds_read_b128 v[150:153], v235 offset:3072
	ds_read_b128 v[126:129], v250
	ds_read_b128 v[202:205], v250 offset:1024
	ds_read_b128 v[194:197], v250 offset:2048
	ds_read_b128 v[198:201], v250 offset:3072
	ds_read_b128 v[186:189], v250 offset:4096
	ds_read_b128 v[190:193], v250 offset:5120
	ds_read_b128 v[178:181], v250 offset:6144
	ds_read_b128 v[182:185], v250 offset:7168
	s_mov_b32 m0, s67
	s_nop 0
	global_load_lds_dwordx4 v0, s[68:69]
	s_add_u32 m0, m0, 0x2000
	s_nop 0
	global_load_lds_dwordx4 v231, s[68:69]
	s_waitcnt vmcnt(8)
.LBB0_737:
	s_waitcnt lgkmcnt(0)
	s_cmp_eq_u32 s0, 40
	s_cselect_b32 s85, s35, s24
	s_cselect_b32 s84, s34, s19
	s_cselect_b32 s71, s77, s26
	s_cselect_b32 s70, s76, s25
	s_barrier
	s_setprio 1
	s_waitcnt lgkmcnt(7)
	v_mfma_f32_16x16x32_bf16 v[98:101], v[158:161], v[126:129], v[162:165]
	v_mfma_f32_16x16x32_bf16 v[114:117], v[170:173], v[126:129], v[154:157]
	s_waitcnt lgkmcnt(5)
	v_mfma_f32_16x16x32_bf16 v[118:121], v[158:161], v[194:197], v[118:121]
	v_mfma_f32_16x16x32_bf16 v[110:113], v[170:173], v[194:197], v[110:113]
	s_waitcnt lgkmcnt(3)
	v_mfma_f32_16x16x32_bf16 v[94:97], v[158:161], v[186:189], v[94:97]
	v_mfma_f32_16x16x32_bf16 v[90:93], v[170:173], v[186:189], v[90:93]
	s_waitcnt lgkmcnt(1)
	v_mfma_f32_16x16x32_bf16 v[78:81], v[158:161], v[178:181], v[78:81]
	v_mfma_f32_16x16x32_bf16 v[74:77], v[170:173], v[178:181], v[74:77]
	v_mfma_f32_16x16x32_bf16 v[98:101], v[166:169], v[202:205], v[98:101]
	v_mfma_f32_16x16x32_bf16 v[114:117], v[174:177], v[202:205], v[114:117]
	v_mfma_f32_16x16x32_bf16 v[118:121], v[166:169], v[198:201], v[118:121]
	v_mfma_f32_16x16x32_bf16 v[110:113], v[174:177], v[198:201], v[110:113]
	v_mfma_f32_16x16x32_bf16 v[94:97], v[166:169], v[190:193], v[94:97]
	v_mfma_f32_16x16x32_bf16 v[90:93], v[174:177], v[190:193], v[90:93]
	s_waitcnt lgkmcnt(0)
	v_mfma_f32_16x16x32_bf16 v[78:81], v[166:169], v[182:185], v[78:81]
	v_mfma_f32_16x16x32_bf16 v[74:77], v[174:177], v[182:185], v[74:77]
	s_setprio 0
	s_setprio 1
	v_mfma_f32_16x16x32_bf16 v[122:125], v[134:137], v[126:129], v[146:149]
	v_mfma_f32_16x16x32_bf16 v[126:129], v[142:145], v[126:129], v[130:133]
	v_mfma_f32_16x16x32_bf16 v[106:109], v[134:137], v[194:197], v[106:109]
	v_mfma_f32_16x16x32_bf16 v[102:105], v[142:145], v[194:197], v[102:105]
	v_mfma_f32_16x16x32_bf16 v[86:89], v[134:137], v[186:189], v[86:89]
	v_mfma_f32_16x16x32_bf16 v[82:85], v[142:145], v[186:189], v[82:85]
	v_mfma_f32_16x16x32_bf16 v[70:73], v[134:137], v[178:181], v[70:73]
	v_mfma_f32_16x16x32_bf16 v[66:69], v[142:145], v[178:181], v[66:69]
	v_mfma_f32_16x16x32_bf16 v[122:125], v[138:141], v[202:205], v[122:125]
	v_mfma_f32_16x16x32_bf16 v[126:129], v[150:153], v[202:205], v[126:129]
	v_mfma_f32_16x16x32_bf16 v[106:109], v[138:141], v[198:201], v[106:109]
	v_mfma_f32_16x16x32_bf16 v[102:105], v[150:153], v[198:201], v[102:105]
	v_mfma_f32_16x16x32_bf16 v[86:89], v[138:141], v[190:193], v[86:89]
	v_mfma_f32_16x16x32_bf16 v[82:85], v[150:153], v[190:193], v[82:85]
	v_mfma_f32_16x16x32_bf16 v[70:73], v[138:141], v[182:185], v[70:73]
	v_mfma_f32_16x16x32_bf16 v[66:69], v[150:153], v[182:185], v[66:69]
	s_setprio 0
	s_barrier
	ds_read_b128 v[186:189], v250 offset:16384
	ds_read_b128 v[190:193], v250 offset:17408
	ds_read_b128 v[178:181], v250 offset:18432
	ds_read_b128 v[182:185], v250 offset:19456
	ds_read_b128 v[154:157], v250 offset:20480
	ds_read_b128 v[162:165], v250 offset:21504
	ds_read_b128 v[130:133], v250 offset:22528
	ds_read_b128 v[146:149], v250 offset:23552
	s_mov_b32 m0, s12
	s_nop 0
	global_load_lds_dwordx4 v230, s[70:71]
	s_add_u32 m0, m0, 0x2000
	s_nop 0
	global_load_lds_dwordx4 v232, s[70:71]
	s_add_u32 s14, s70, 0xb0000
	s_addc_u32 s15, s71, 0
	s_mov_b32 m0, s13
	s_nop 0
	global_load_lds_dwordx4 v230, s[14:15]
	s_add_u32 m0, m0, 0x2000
	s_nop 0
	global_load_lds_dwordx4 v232, s[14:15]
	s_mov_b32 m0, s10
	s_nop 0
	global_load_lds_dwordx4 v0, s[84:85]
	s_add_u32 m0, m0, 0x2000
	s_nop 0
	global_load_lds_dwordx4 v231, s[84:85]
	s_waitcnt vmcnt(8)
; #define PG8_STAGE(bufoff, gbase, voff) glds16s2((voff)[0], (voff)[1], (const void*)(gbase), ldsn + (unsigned)(bufoff))
; #define PG8_LDA(dst, b, h) do { _Pragma("unroll") for (int m = 0; m < 4; ++m) _Pragma("unroll") for (int k = 0; k < 2; ++k) dst[m][k] = *(const LAS bf16x8*)(lds + PG8_SA(b, h) + aoff + m * 2048 + k * 1024); } while (0)
; #define PG8_LDB(dst, b, h) do { _Pragma("unroll") for (int n = 0; n < 2; ++n) _Pragma("unroll") for (int k = 0; k < 2; ++k) dst[n][k] = *(const LAS bf16x8*)(lds + PG8_SB(b, h) + boff + n * 2048 + k * 1024); } while (0)
; #define PG8_MMA(ai, bj, At, Bt) do { __builtin_amdgcn_s_setprio(1); _Pragma("unroll") for (int m = 0; m < 4; ++m) _Pragma("unroll") for (int n = 0; n < 2; ++n) _Pragma("unroll") for (int k = 0; k < 2; ++k) \
;         acc[ai][bj][m][n] = __builtin_amdgcn_mfma_f32_16x16x32_bf16(Bt[n][k], At[m][k], acc[ai][bj][m][n], 0, 0, 0); __builtin_amdgcn_s_setprio(0); } while (0)
; #define PG8_WAIT_V(n) asm volatile("s_waitcnt vmcnt(" #n ")" ::: "memory")
; #define PG8_WAIT_L(n) asm volatile("s_waitcnt lgkmcnt(" #n ")" ::: "memory")
; #define PG8_BAR __builtin_amdgcn_s_barrier()
; #define PG8_SCHED __builtin_amdgcn_sched_barrier(0)
; template <class Epi, bool ALIGN_EPI, bool EARLY_DRAIN = true, class Pre = NoPre>
; __device__ __forceinline__ void gemm_phase(LAS unsigned char* lds, const Gemm g, const StaticOrder& S, const Epi& E, int wv, const Pre& pre = Pre()) {
;     ...
;             PG8_WAIT_L(0); PG8_BAR; PG8_MMA(1, 0, At, B0); PG8_MMA(1, 1, At, B1); PG8_BAR; PG8_SCHED;
;             PG8_LDB(B0, 1, 0); PG8_LDB(B1, 1, 1); PG8_SCHED; PG8_LDA(At, 1, 0); PG8_STAGE(PG8_SA(0, 1), a2 + ahs, voffA);
;             if (!lf_) PG8_WAIT_V(8);
.LBB0_739:
	s_waitcnt lgkmcnt(0)
	s_barrier
	s_setprio 1
	s_waitcnt lgkmcnt(7)
	v_mfma_f32_16x16x32_bf16 v[62:65], v[158:161], v[186:189], v[62:65]
	v_mfma_f32_16x16x32_bf16 v[58:61], v[170:173], v[186:189], v[58:61]
	s_waitcnt lgkmcnt(5)
	v_mfma_f32_16x16x32_bf16 v[46:49], v[158:161], v[178:181], v[46:49]
	v_mfma_f32_16x16x32_bf16 v[42:45], v[170:173], v[178:181], v[42:45]
	s_waitcnt lgkmcnt(3)
	v_mfma_f32_16x16x32_bf16 v[30:33], v[158:161], v[154:157], v[30:33]
	v_mfma_f32_16x16x32_bf16 v[26:29], v[170:173], v[154:157], v[26:29]
	s_waitcnt lgkmcnt(1)
	v_mfma_f32_16x16x32_bf16 v[14:17], v[158:161], v[130:133], v[14:17]
	v_mfma_f32_16x16x32_bf16 v[10:13], v[170:173], v[130:133], v[10:13]
	v_mfma_f32_16x16x32_bf16 v[62:65], v[166:169], v[190:193], v[62:65]
	v_mfma_f32_16x16x32_bf16 v[58:61], v[174:177], v[190:193], v[58:61]
	v_mfma_f32_16x16x32_bf16 v[46:49], v[166:169], v[182:185], v[46:49]
	v_mfma_f32_16x16x32_bf16 v[42:45], v[174:177], v[182:185], v[42:45]
	v_mfma_f32_16x16x32_bf16 v[30:33], v[166:169], v[162:165], v[30:33]
	v_mfma_f32_16x16x32_bf16 v[26:29], v[174:177], v[162:165], v[26:29]
	s_waitcnt lgkmcnt(0)
	v_mfma_f32_16x16x32_bf16 v[14:17], v[166:169], v[146:149], v[14:17]
	v_mfma_f32_16x16x32_bf16 v[10:13], v[174:177], v[146:149], v[10:13]
	s_setprio 0
	s_setprio 1
	v_mfma_f32_16x16x32_bf16 v[54:57], v[134:137], v[186:189], v[54:57]
	v_mfma_f32_16x16x32_bf16 v[50:53], v[142:145], v[186:189], v[50:53]
	v_mfma_f32_16x16x32_bf16 v[38:41], v[134:137], v[178:181], v[38:41]
	v_mfma_f32_16x16x32_bf16 v[34:37], v[142:145], v[178:181], v[34:37]
	v_mfma_f32_16x16x32_bf16 v[22:25], v[134:137], v[154:157], v[22:25]
	v_mfma_f32_16x16x32_bf16 v[18:21], v[142:145], v[154:157], v[18:21]
	v_mfma_f32_16x16x32_bf16 v[6:9], v[134:137], v[130:133], v[6:9]
	v_mfma_f32_16x16x32_bf16 v[2:5], v[142:145], v[130:133], v[2:5]
	v_mfma_f32_16x16x32_bf16 v[54:57], v[138:141], v[190:193], v[54:57]
	v_mfma_f32_16x16x32_bf16 v[50:53], v[150:153], v[190:193], v[50:53]
	v_mfma_f32_16x16x32_bf16 v[38:41], v[138:141], v[182:185], v[38:41]
	v_mfma_f32_16x16x32_bf16 v[34:37], v[150:153], v[182:185], v[34:37]
	v_mfma_f32_16x16x32_bf16 v[22:25], v[138:141], v[162:165], v[22:25]
	v_mfma_f32_16x16x32_bf16 v[18:21], v[150:153], v[162:165], v[18:21]
	v_mfma_f32_16x16x32_bf16 v[6:9], v[138:141], v[146:149], v[6:9]
	v_mfma_f32_16x16x32_bf16 v[2:5], v[150:153], v[146:149], v[2:5]
	s_setprio 0
	s_barrier
	ds_read_b128 v[158:161], v244
	ds_read_b128 v[166:169], v244 offset:1024
	ds_read_b128 v[170:173], v244 offset:2048
	ds_read_b128 v[174:177], v244 offset:3072
	ds_read_b128 v[134:137], v245
	ds_read_b128 v[138:141], v245 offset:1024
	ds_read_b128 v[142:145], v245 offset:2048
	ds_read_b128 v[150:153], v245 offset:3072
	ds_read_b128 v[130:133], v250 offset:32768
	ds_read_b128 v[202:205], v250 offset:33792
	ds_read_b128 v[194:197], v250 offset:34816
	ds_read_b128 v[198:201], v250 offset:35840
	ds_read_b128 v[186:189], v250 offset:36864
	ds_read_b128 v[190:193], v250 offset:37888
	ds_read_b128 v[178:181], v250 offset:38912
	ds_read_b128 v[182:185], v250 offset:39936
	s_add_u32 s14, s84, 0xb0000
	s_addc_u32 s15, s85, 0
	s_mov_b32 m0, s99
	s_nop 0
	global_load_lds_dwordx4 v0, s[14:15]
	s_add_u32 m0, m0, 0x2000
	s_nop 0
	global_load_lds_dwordx4 v231, s[14:15]
	s_waitcnt vmcnt(8)
	s_branch .LBB0_734
	s_nop 0
	s_nop 0
	s_nop 0
	s_nop 0
	s_nop 0
	s_nop 0
	s_nop 0
	s_nop 0
	s_nop 0
	s_nop 0
	s_nop 0
	s_nop 0
	s_nop 0
